# v9 with the scan-phase conversion software-pipelined across loader iterations (process the item loaded one iteration earlier, then issue the next loads; no exposed HBM latency in the loader)
# baseline (speedup 1.0000x reference)
.LBB0_208:
	s_cmp_eq_u32 s53, 1
	s_cbranch_scc0 .Lcis_b_done
	s_waitcnt vmcnt(4)
	s_cmp_eq_u32 s61, 2
	s_cbranch_scc1 .Lcis_b_flat
	s_cmp_eq_u32 s61, 0
	s_cbranch_scc1 .Lcis_b_nogs
	v_mul_f32_e32 v232, v232, v248
	v_mul_f32_e32 v233, v233, v248
	v_mul_f32_e32 v234, v234, v248
	v_mul_f32_e32 v235, v235, v248
	v_mul_f32_e32 v236, v236, v249
	v_mul_f32_e32 v237, v237, v249
	v_mul_f32_e32 v238, v238, v249
	v_mul_f32_e32 v239, v239, v249
	v_mul_f32_e32 v240, v240, v250
	v_mul_f32_e32 v241, v241, v250
	v_mul_f32_e32 v242, v242, v250
	v_mul_f32_e32 v243, v243, v250
	v_mul_f32_e32 v244, v244, v251
	v_mul_f32_e32 v245, v245, v251
	v_mul_f32_e32 v246, v246, v251
	v_mul_f32_e32 v247, v247, v251

.Lcis_b_next:
.Lcis_b_done:
	s_mov_b32 s53, 0
	v_readlane_b32 s52, v224, 30
	s_nop 3
	s_cmp_lt_u32 s55, s52
	s_cbranch_scc0 .Lcis_a_done
	s_mov_b32 s53, 1
	s_cmp_lt_u32 s55, 0x1000
	s_cbranch_scc1 .Lcis_j_wout
	s_cmp_lt_u32 s55, 0x2000
	s_cbranch_scc1 .Lcis_j_gate
	s_cmp_lt_u32 s55, 0x6000
	s_cbranch_scc1 .Lcis_j_down
	s_cmp_lt_u32 s55, 0xa000
	s_cbranch_scc1 .Lcis_j_up
	s_cmp_lt_u32 s55, 0xb000
	s_cbranch_scc1 .Lcis_j_p

.Lcis_j_p:
	s_sub_u32 s51, s55, 0xa000
	s_movk_i32 s61, 2
	v_readlane_b32 s58, v224, 20
	v_readlane_b32 s59, v224, 21
	v_readlane_b32 s64, v224, 22
	v_readlane_b32 s65, v224, 23
	s_lshl_b32 s52, s51, 12
	s_add_u32 s58, s58, s52
	s_addc_u32 s59, s59, 0
	s_lshl_b32 s52, s51, 11
	s_add_u32 s64, s64, s52
	s_addc_u32 s65, s65, 0
	v_lshlrev_b32_e32 v216, 5, v197
	global_load_dwordx4 v[232:235], v216, s[58:59]
	global_load_dwordx4 v[236:239], v216, s[58:59] offset:16
	global_load_dwordx4 v[240:243], v216, s[58:59] offset:2048
	global_load_dwordx4 v[244:247], v216, s[58:59] offset:2064
.Lcis_a_inc:
	s_lshl_b32 s50, s80, 2
	s_add_u32 s55, s55, s50
.Lcis_a_done:
	v_lshlrev_b32_e32 v156, 16, v104
	v_and_b32_e32 v104, 0xffff0000, v104
	v_lshlrev_b32_e32 v178, 16, v105
	v_and_b32_e32 v105, 0xffff0000, v105
	v_lshlrev_b32_e32 v179, 16, v106
	v_and_b32_e32 v106, 0xffff0000, v106
	v_lshlrev_b32_e32 v180, 16, v107
	v_and_b32_e32 v107, 0xffff0000, v107
	v_cmp_eq_u32_e64 s[48:49], s20, v136
	v_lshlrev_b32_e32 v162, 16, v100
	v_and_b32_e32 v163, 0xffff0000, v100
	v_lshlrev_b32_e32 v176, 16, v101
	v_and_b32_e32 v177, 0xffff0000, v101
	v_lshlrev_b32_e32 v100, 16, v102
	v_and_b32_e32 v101, 0xffff0000, v102
	v_lshlrev_b32_e32 v102, 16, v103
	v_and_b32_e32 v103, 0xffff0000, v103
	v_cndmask_b32_e64 v180, v180, 0, s[48:49]
	v_cndmask_b32_e64 v181, v107, 0, s[48:49]
	v_cndmask_b32_e64 v182, v179, 0, s[48:49]
	v_cndmask_b32_e64 v179, v106, 0, s[48:49]
	v_cndmask_b32_e64 v106, v178, 0, s[48:49]
	v_cndmask_b32_e64 v107, v105, 0, s[48:49]
	v_cndmask_b32_e64 v156, v156, 0, s[48:49]
	v_cndmask_b32_e64 v104, v104, 0, s[48:49]
	v_sub_f32_e32 v105, v104, v163
	v_sub_f32_e32 v104, v156, v162
	v_sub_f32_e32 v107, v107, v177
	v_sub_f32_e32 v106, v106, v176
	v_sub_f32_e32 v179, v179, v101
	v_sub_f32_e32 v178, v182, v100
	v_sub_f32_e32 v181, v181, v103
	v_sub_f32_e32 v180, v180, v102
	v_pk_fma_f32 v[102:103], v[38:39], v[180:181], v[102:103]
	v_pk_fma_f32 v[100:101], v[36:37], v[178:179], v[100:101]
	v_pk_fma_f32 v[106:107], v[34:35], v[106:107], v[176:177]
	s_and_b64 vcc, exec, s[44:45]
	v_pk_fma_f32 v[104:105], v[32:33], v[104:105], v[162:163]
	s_cbranch_vccnz .LBB0_210
	v_lshlrev_b32_e32 v156, 16, v92
	v_and_b32_e32 v92, 0xffff0000, v92
	v_lshlrev_b32_e32 v162, 16, v93
	v_and_b32_e32 v163, 0xffff0000, v93
	v_lshlrev_b32_e32 v176, 16, v94
	v_and_b32_e32 v177, 0xffff0000, v94
	v_lshlrev_b32_e32 v178, 16, v95
	v_and_b32_e32 v179, 0xffff0000, v95
	v_sub_f32_e32 v93, v92, v105
	v_sub_f32_e32 v92, v156, v104
	v_sub_f32_e32 v95, v163, v107
	v_sub_f32_e32 v94, v162, v106
	v_sub_f32_e32 v163, v177, v101
	v_sub_f32_e32 v162, v176, v100
	v_sub_f32_e32 v177, v179, v103
	v_sub_f32_e32 v176, v178, v102
	v_lshlrev_b32_e32 v178, 16, v88
	v_and_b32_e32 v179, 0xffff0000, v88
	v_lshlrev_b32_e32 v88, 16, v89
	v_and_b32_e32 v89, 0xffff0000, v89
	v_lshlrev_b32_e32 v180, 16, v90
	v_and_b32_e32 v181, 0xffff0000, v90
	v_lshlrev_b32_e32 v90, 16, v91
	v_and_b32_e32 v91, 0xffff0000, v91
	v_pk_fma_f32 v[102:103], v[176:177], v[90:91], v[102:103]
	v_pk_fma_f32 v[100:101], v[162:163], v[180:181], v[100:101]
	v_pk_fma_f32 v[106:107], v[94:95], v[88:89], v[106:107]
	v_pk_fma_f32 v[104:105], v[92:93], v[178:179], v[104:105]
